# GEMM phases: one static s_setprio 1 for waves 4-7 for the whole phase (reset at phase end), no per-phase flips
# speedup vs baseline: 1.0342x; 1.0074x over previous
; __device__ __forceinline__ int fresh_tid() { int t = threadIdx.x; asm volatile("" : "+v"(t)); return t; }
; #define PG8_STAGE(bufoff, gbase, voff) do { _Pragma("unroll") for (int _i = 0; _i < 2; ++_i) \
;         __builtin_amdgcn_global_load_lds((const unsigned*)((const char*)(gbase) + (voff)[_i]), (LAS unsigned*)(lds + (bufoff) + ldsw + _i * 8192), 16, 0, 0); } while (0)
; #define PG8_WAIT_V(n) asm volatile("s_waitcnt vmcnt(" #n ")" ::: "memory")
; #define PG8_BAR __builtin_amdgcn_s_barrier()
; template <class Epi>
; __device__ __forceinline__ void gemm_phase(LAS unsigned char* lds, const Gemm g, const StaticOrder& S, const Epi& E) {
;     const int tid = fresh_tid(), wid = __builtin_amdgcn_readfirstlane(tid >> 6), lane = tid & 63, wr = wid >> 2, wc = wid & 3, fr = lane & 15, fq = lane >> 4;
;     const int K = g.K, nt = K / BK;
;     unsigned voffA[2], voffB[2];
; #pragma unroll
;     for (int i = 0; i < 2; ++i) { int R, C; stage_rc(tid * 16 + i * 8192, R, C); const int Rb = (R & ~31) + perm32(R & 31);
;         voffA[i] = (unsigned)(R * K + C) * 2u; voffB[i] = (unsigned)(Rb * K + C) * 2u; }
;     const size_t kstep = (size_t)(BK * 2);
;     const size_t hstep = (size_t)HALF * K * 2;
;     const size_t tstep = 2 * hstep;
;     const unsigned ldsw = (unsigned)wid * 1024u;
;     const int aoff = lds_byte(wr * 64 + fr, fq * 8), boff = lds_byte(wc * 32 + fr, fq * 8);
;     ...
;     Unit cur, nxt; int ui = 0;
;     if (!S.next(0, cur)) return;
;     f32x4 acc[2][2][4][2];
; #pragma unroll
;     for (int a = 0; a < 2; ++a)
; #pragma unroll
;         for (int b = 0; b < 2; ++b)
; #pragma unroll
;             for (int m = 0; m < 4; ++m)
; #pragma unroll
;                 for (int n = 0; n < 2; ++n) acc[a][b][m][n] = (f32x4){0.f, 0.f, 0.f, 0.f};
;     bf16x8 At[4][2], B0[2][2], B1[2][2];
;     const char* cA = (const char*)g.A + (size_t)cur.pm * tstep; const char* cB = (const char*)g.Bt + (size_t)cur.pn * tstep;
;     PG8_STAGE(PG8_SB(0, 0), cB, voffB); PG8_STAGE(PG8_SA(0, 0), cA, voffA); PG8_STAGE(PG8_SB(0, 1), cB + hstep, voffB); PG8_STAGE(PG8_SA(0, 1), cA + hstep, voffA);
;     if (wr == 1) PG8_BAR;
;     PG8_WAIT_V(4); PG8_BAR;
;     PG8_STAGE(PG8_SB(1, 0), cB + kstep, voffB); PG8_STAGE(PG8_SA(1, 0), cA + kstep, voffA); PG8_STAGE(PG8_SB(1, 1), cB + hstep + kstep, voffB);
;     PG8_WAIT_V(6); PG8_BAR;
.LBB0_196:
	v_readlane_b32 s8, v232, 0
	s_lshl_b32 s3, s8, 13
	s_add_u32 s4, s16, 0xbb50000
	s_addc_u32 s5, s17, 0
	s_lshl_b32 s61, s60, 11
	s_mul_i32 s9, s8, 0x6000000
	s_or_b32 s8, s3, s61
	v_writelane_b32 v232, s3, 6
	s_lshl_b32 s3, s8, 12
	s_add_u32 s97, s4, s3
	v_writelane_b32 v232, s4, 7
	s_addc_u32 s94, s5, 0
	s_lshl_b32 s3, s8, 2
	s_add_u32 s3, s16, s3
	v_writelane_b32 v232, s5, 8
	s_addc_u32 s4, s17, 0
	s_add_u32 s14, s3, 0xbb40000
	s_addc_u32 s15, s4, 0
	s_add_u32 s3, s16, s9
	s_addc_u32 s4, s17, 0
	v_writelane_b32 v232, s8, 9
	s_add_u32 s8, s3, 0x13b50000
	v_writelane_b32 v232, s9, 10
	s_addc_u32 s9, s4, 0
	s_mul_i32 s3, s60, 0x1800000
	v_writelane_b32 v232, s60, 11
	s_add_u32 s20, s8, s3
	v_writelane_b32 v232, s8, 12
	s_addc_u32 s21, s9, 0
	s_ashr_i32 s12, s2, 3
	s_ashr_i32 s96, s67, 3
	s_cmpk_lt_i32 s12, 0x160
	v_writelane_b32 v232, s9, 13
	v_mov_b32_e32 v9, v158
	s_cselect_b64 s[4:5], -1, 0
	v_writelane_b32 v232, s4, 14
	v_readfirstlane_b32 s3, v9
	s_cmpk_gt_i32 s12, 0x15f
	v_writelane_b32 v232, s5, 15
	s_cbranch_scc1 .LBB0_208
	v_lshlrev_b32_e32 v0, 4, v9
	v_add_u32_e32 v1, 0x2000, v0
	v_ashrrev_i32_e32 v2, 31, v1
	v_lshrrev_b32_e32 v2, 22, v2
	v_add_u32_e32 v2, v1, v2
	v_ashrrev_i32_e32 v8, 10, v2
	v_mul_i32_i24_e32 v2, 0x400, v8
	v_sub_u32_e32 v1, v1, v2
	v_lshrrev_b32_e32 v2, 4, v1
	v_bitop3_b32 v1, v2, v1, 32 bitop3:0x6c
	v_ashrrev_i32_e32 v2, 31, v1
	v_lshrrev_b32_e32 v2, 26, v2
	v_add_u32_e32 v2, v1, v2
	v_lshlrev_b32_e32 v3, 3, v8
	v_ashrrev_i32_e32 v10, 6, v2
	v_and_b32_e32 v3, -16, v3
	v_add_u32_e32 v3, v10, v3
	v_and_b32_e32 v4, 3, v10
	s_mov_b32 s4, 0xfffe0
	v_lshrrev_b32_e32 v5, 2, v3
	v_lshlrev_b32_e32 v6, 1, v3
	v_and_b32_e32 v2, 0xc0, v2
	v_and_or_b32 v4, v3, s4, v4
	v_and_b32_e32 v5, 4, v5
	v_and_b32_e32 v6, 24, v6
	v_sub_u32_e32 v1, v1, v2
	v_mov_b32_e32 v2, 1
	v_or3_b32 v4, v4, v5, v6
	v_lshlrev_b32_e32 v5, 5, v8
	v_ashrrev_i16_sdwa v1, v2, sext(v1) dst_sel:DWORD dst_unused:UNUSED_PAD src0_sel:DWORD src1_sel:BYTE_0
	v_and_b32_e32 v5, 32, v5
	v_bfe_i32 v11, v1, 0, 16
	v_add_lshl_u32 v1, v5, v11, 1
	v_lshl_add_u32 v128, v4, 12, v1
	v_lshl_add_u32 v130, v3, 12, v1
	v_bfe_i32 v1, v9, 27, 1
	v_lshrrev_b32_e32 v1, 22, v1
	v_add_u32_e32 v1, v0, v1
	v_and_b32_e32 v1, 0xfffffc00, v1
	v_sub_u32_e32 v0, v0, v1
	v_lshrrev_b32_e32 v1, 4, v0
	v_bitop3_b32 v1, v1, v0, 32 bitop3:0x6c
	v_ashrrev_i32_e32 v0, 31, v0
	v_lshrrev_b32_e32 v0, 26, v0
	v_add_u32_e32 v0, v1, v0
	v_ashrrev_i32_e32 v12, 6, v0
	v_ashrrev_i32_e32 v0, 31, v9
	v_lshrrev_b32_e32 v0, 26, v0
	v_add_u32_e32 v0, v9, v0
	v_ashrrev_i32_e32 v13, 6, v0
	v_lshlrev_b32_e32 v0, 3, v13
	v_and_b32_e32 v0, -16, v0
	v_add_u32_e32 v0, v12, v0
	v_and_b32_e32 v3, 3, v12
	s_mul_hi_i32 s9, s12, 0x2e8ba2e9
	v_and_or_b32 v3, v0, s4, v3
	s_lshr_b32 s4, s9, 31
	s_ashr_i32 s9, s9, 6
	s_add_i32 s4, s9, s4
	s_lshl_b32 s9, s4, 3
	s_mulk_i32 s4, 0x160
	s_sub_i32 s11, s12, s4
	s_bfe_u32 s4, s11, 0x3001c
	s_add_i32 s13, s11, s4
	s_sext_i32_i16 s4, s13
	s_and_b32 s13, s13, 0xfff8
	v_lshrrev_b32_e32 v4, 2, v0
	v_lshlrev_b32_e32 v5, 1, v0
	s_sub_i32 s11, s11, s13
	v_and_b32_e32 v4, 4, v4
	v_and_b32_e32 v5, 24, v5
	s_sext_i32_i16 s11, s11
	s_ashr_i32 s5, s3, 8
	v_or3_b32 v3, v3, v4, v5
	v_mul_i32_i24_e32 v5, 64, v12
	s_lshr_b32 s4, s4, 3
	s_add_i32 s40, s9, s11
	s_ashr_i32 s8, s3, 6
	v_sub_u32_e32 v1, v1, v5
	s_ashr_i32 s41, s40, 31
	s_bfe_i64 s[24:25], s[4:5], 0x100000
	s_lshl_b32 s10, s8, 10
	v_lshlrev_b32_e32 v4, 5, v13
	v_ashrrev_i16_sdwa v1, v2, sext(v1) dst_sel:DWORD dst_unused:UNUSED_PAD src0_sel:DWORD src1_sel:BYTE_0
	s_lshl_b64 s[22:23], s[40:41], 20
	s_lshl_b64 s[24:25], s[24:25], 20
	v_and_b32_e32 v4, 32, v4
	v_bfe_i32 v14, v1, 0, 16
	s_add_u32 s44, s16, s24
	v_add_lshl_u32 v1, v4, v14, 1
	s_addc_u32 s45, s17, s25
	s_add_i32 s11, s10, 0
	v_lshl_add_u32 v132, v3, 12, v1
	s_add_i32 m0, s11, 0x10000
	v_lshl_add_u32 v134, v0, 12, v1
	global_load_lds_dwordx4 v132, s[44:45]
	s_add_i32 m0, s11, 0x12000
	s_add_u32 s42, s97, s22
	global_load_lds_dwordx4 v128, s[44:45]
	s_addc_u32 s43, s94, s23
	s_mov_b32 m0, s11
	s_add_i32 s13, s11, 0x2000
	global_load_lds_dwordx4 v134, s[42:43]
	s_mov_b32 m0, s13
	s_add_u32 s22, s44, 0x80000
	global_load_lds_dwordx4 v130, s[42:43]
	s_addc_u32 s23, s45, 0
	s_add_i32 m0, s11, 0x14000
	v_mov_b32_e32 v133, 0
	global_load_lds_dwordx4 v132, s[22:23]
	s_add_i32 m0, s11, 0x16000
	v_mov_b32_e32 v129, v133
	global_load_lds_dwordx4 v128, s[22:23]
	s_add_u32 s22, s42, 0x80000
	s_addc_u32 s23, s43, 0
	s_add_i32 s30, s11, 0x4000
	s_mov_b32 m0, s30
	s_add_i32 s31, s11, 0x6000
	global_load_lds_dwordx4 v134, s[22:23]
	s_mov_b32 m0, s31
	v_mov_b32_e32 v135, v133
	global_load_lds_dwordx4 v130, s[22:23]
	v_mov_b32_e32 v131, v133
	s_mov_b32 s33, 0
	v_lshl_add_u64 v[6:7], s[44:45], 0, v[132:133]
	v_lshl_add_u64 v[4:5], s[44:45], 0, v[128:129]
	v_lshl_add_u64 v[2:3], s[42:43], 0, v[134:135]
	s_cmp_lg_u32 s5, 1
	v_lshl_add_u64 v[0:1], s[42:43], 0, v[130:131]
	s_cbranch_scc1 .LBB0_199
	s_barrier
	s_setprio 1

; #define PG8_WAIT_V(n) asm volatile("s_waitcnt vmcnt(" #n ")" ::: "memory")
; #define PG8_BAR __builtin_amdgcn_s_barrier()
; template <class Epi>
; __device__ __forceinline__ void gemm_phase(LAS unsigned char* lds, const Gemm g, const StaticOrder& S, const Epi& E) {
;     ...
;     PG8_WAIT_V(0);
;     if (wr == 0) PG8_BAR;
;     PG8_BAR;
.LBB0_207:
	s_barrier
	s_setprio 0

; __device__ __forceinline__ int fresh_tid() { int t = threadIdx.x; asm volatile("" : "+v"(t)); return t; }
; #define PG8_WAIT_V(n) asm volatile("s_waitcnt vmcnt(" #n ")" ::: "memory")
; #define PG8_BAR __builtin_amdgcn_s_barrier()
; template <class Epi>
; __device__ __forceinline__ void gemm_phase(LAS unsigned char* lds, const Gemm g, const StaticOrder& S, const Epi& E) {
;     const int tid = fresh_tid(), wid = __builtin_amdgcn_readfirstlane(tid >> 6), lane = tid & 63, wr = wid >> 2, wc = wid & 3, fr = lane & 15, fq = lane >> 4;
;     const int K = g.K, nt = K / BK;
;     unsigned voffA[2], voffB[2];
; #pragma unroll
;     for (int i = 0; i < 2; ++i) { int R, C; stage_rc(tid * 16 + i * 8192, R, C); const int Rb = (R & ~31) + perm32(R & 31);
;         voffA[i] = (unsigned)(R * K + C) * 2u; voffB[i] = (unsigned)(Rb * K + C) * 2u; }
;     const size_t kstep = (size_t)(BK * 2);
;     const size_t hstep = (size_t)HALF * K * 2;
;     const size_t tstep = 2 * hstep;
;     const unsigned ldsw = (unsigned)wid * 1024u;
;     const int aoff = lds_byte(wr * 64 + fr, fq * 8), boff = lds_byte(wc * 32 + fr, fq * 8);
;     ...
;     Unit cur, nxt; int ui = 0;
;     if (!S.next(0, cur)) return;
;     f32x4 acc[2][2][4][2];
; #pragma unroll
;     for (int a = 0; a < 2; ++a)
; #pragma unroll
;         for (int b = 0; b < 2; ++b)
; #pragma unroll
;             for (int m = 0; m < 4; ++m)
; #pragma unroll
;                 for (int n = 0; n < 2; ++n) acc[a][b][m][n] = (f32x4){0.f, 0.f, 0.f, 0.f};
;     bf16x8 At[4][2], B0[2][2], B1[2][2];
;     const char* cA = (const char*)g.A + (size_t)cur.pm * tstep; const char* cB = (const char*)g.Bt + (size_t)cur.pn * tstep;
;     PG8_STAGE(PG8_SB(0, 0), cB, voffB); PG8_STAGE(PG8_SA(0, 0), cA, voffA); PG8_STAGE(PG8_SB(0, 1), cB + hstep, voffB); PG8_STAGE(PG8_SA(0, 1), cA + hstep, voffA);
;     if (wr == 1) PG8_BAR;
;     PG8_WAIT_V(4); PG8_BAR;
;     PG8_STAGE(PG8_SB(1, 0), cB + kstep, voffB); PG8_STAGE(PG8_SA(1, 0), cA + kstep, voffA); PG8_STAGE(PG8_SB(1, 1), cB + hstep + kstep, voffB);
;     PG8_WAIT_V(6); PG8_BAR;
; __global__ __launch_bounds__(512, 2) void fwd_megakernel(Params P) {
;     ...
;     { pg8::Gemm g{Xc, (const bf16_t*)(ws + OFF_W1B), CR, DM, DFF}; S.init(CR, DM, nc, ci, 1); pg8::EpiPlain E{Fc, DM}; pg8::gemm_phase(lds, g, S, E); }
.LBB0_272:
	s_or_b64 exec, exec, s[4:5]
	s_add_u32 s4, s16, 0xfb50000
	s_addc_u32 s5, s17, 0
	s_lshl_b32 s3, s3, 1
	s_add_u32 s24, s4, s3
	v_writelane_b32 v232, s4, 16
	s_addc_u32 s25, s5, 0
	s_cmp_lt_i32 s12, 64
	v_writelane_b32 v232, s5, 17
	s_cselect_b64 s[4:5], -1, 0
	v_writelane_b32 v232, s4, 18
	v_mov_b32_e32 v8, v158
	s_waitcnt lgkmcnt(0)
	v_writelane_b32 v232, s5, 19
	s_barrier
	s_cmp_gt_i32 s12, 63
	v_readfirstlane_b32 s3, v8
	v_writelane_b32 v232, s62, 20
	v_writelane_b32 v232, s61, 21
	s_cbranch_scc1 .LBB0_288
	v_lshlrev_b32_e32 v0, 4, v8
	v_add_u32_e32 v1, 0x2000, v0
	v_ashrrev_i32_e32 v2, 31, v1
	v_lshrrev_b32_e32 v2, 22, v2
	v_add_u32_e32 v2, v1, v2
	v_ashrrev_i32_e32 v9, 10, v2
	v_mul_i32_i24_e32 v2, 0x400, v9
	v_sub_u32_e32 v1, v1, v2
	v_lshrrev_b32_e32 v2, 4, v1
	v_bitop3_b32 v1, v2, v1, 32 bitop3:0x6c
	v_ashrrev_i32_e32 v2, 31, v1
	v_lshrrev_b32_e32 v2, 26, v2
	v_add_u32_e32 v2, v1, v2
	v_lshlrev_b32_e32 v3, 3, v9
	v_ashrrev_i32_e32 v10, 6, v2
	v_and_b32_e32 v3, -16, v3
	v_add_u32_e32 v3, v10, v3
	v_and_b32_e32 v4, 3, v10
	s_mov_b32 s7, 0x7fffe0
	v_lshrrev_b32_e32 v5, 2, v3
	v_lshlrev_b32_e32 v6, 1, v3
	v_and_b32_e32 v2, 0xc0, v2
	v_and_or_b32 v4, v3, s7, v4
	v_and_b32_e32 v5, 4, v5
	v_and_b32_e32 v6, 24, v6
	v_sub_u32_e32 v1, v1, v2
	v_mov_b32_e32 v2, 1
	v_or3_b32 v4, v4, v5, v6
	v_lshlrev_b32_e32 v5, 5, v9
	v_ashrrev_i16_sdwa v1, v2, sext(v1) dst_sel:DWORD dst_unused:UNUSED_PAD src0_sel:DWORD src1_sel:BYTE_0
	s_movk_i32 s4, 0x1600
	v_and_b32_e32 v11, 32, v5
	v_bfe_i32 v12, v1, 0, 16
	v_mul_u32_u24_e32 v4, 0x1600, v4
	v_add_u32_e32 v1, v11, v12
	v_mul_lo_u32 v3, v3, s4
	v_add_lshl_u32 v128, v4, v1, 1
	v_add_lshl_u32 v130, v1, v3, 1
	v_bfe_i32 v1, v8, 27, 1
	v_lshrrev_b32_e32 v1, 22, v1
	v_add_u32_e32 v1, v0, v1
	v_and_b32_e32 v1, 0xfffffc00, v1
	v_sub_u32_e32 v0, v0, v1
	v_lshrrev_b32_e32 v1, 4, v0
	v_bitop3_b32 v1, v1, v0, 32 bitop3:0x6c
	v_ashrrev_i32_e32 v0, 31, v0
	v_lshrrev_b32_e32 v0, 26, v0
	v_add_u32_e32 v0, v1, v0
	v_ashrrev_i32_e32 v13, 6, v0
	v_ashrrev_i32_e32 v0, 31, v8
	v_lshrrev_b32_e32 v0, 26, v0
	v_add_u32_e32 v0, v8, v0
	v_ashrrev_i32_e32 v14, 6, v0
	v_lshlrev_b32_e32 v0, 3, v14
	s_add_u32 s10, s16, 0x2c00000
	v_and_b32_e32 v0, -16, v0
	s_addc_u32 s11, s17, 0
	v_add_u32_e32 v0, v13, v0
	v_and_b32_e32 v3, 3, v13
	s_ashr_i32 s22, s12, 31
	v_and_or_b32 v3, v0, s7, v3
	s_lshr_b32 s7, s22, 26
	s_add_i32 s7, s12, s7
	s_ashr_i32 s8, s7, 6
	s_and_b32 s7, s7, 0xffc0
	s_sub_i32 s7, s12, s7
	s_lshl_b32 s9, s8, 3
	s_bfe_i32 s8, s7, 0x80000
	v_lshrrev_b32_e32 v4, 2, v0
	v_lshlrev_b32_e32 v5, 1, v0
	s_bfe_u32 s8, s8, 0x3000c
	v_and_b32_e32 v4, 4, v4
	v_and_b32_e32 v5, 24, v5
	s_add_i32 s23, s7, s8
	v_or3_b32 v3, v3, v4, v5
	v_lshlrev_b32_e32 v4, 5, v14
	s_bfe_i32 s8, s23, 0x80000
	s_and_b32 s23, s23, 0xf8
	v_and_b32_e32 v15, 32, v4
	v_mul_i32_i24_e32 v4, 64, v13
	s_sext_i32_i16 s26, s8
	s_sub_i32 s7, s7, s23
	s_ashr_i32 s6, s3, 6
	v_sub_u32_e32 v1, v1, v4
	s_sext_i32_i8 s7, s7
	s_ashr_i32 s23, s26, 3
	s_ashr_i32 s5, s3, 8
	s_lshl_b32 s13, s6, 10
	v_ashrrev_i16_sdwa v1, v2, sext(v1) dst_sel:DWORD dst_unused:UNUSED_PAD src0_sel:DWORD src1_sel:BYTE_0
	s_lshr_b32 s8, s26, 3
	s_add_i32 s61, s9, s7
	s_mul_hi_i32 s26, s23, 0x2c0000
	s_mul_i32 s23, s23, 0x2c0000
	v_bfe_i32 v16, v1, 0, 16
	s_add_u32 s50, s10, s23
	v_mul_u32_u24_e32 v3, 0x1600, v3
	v_add_u32_e32 v1, v15, v16
	s_addc_u32 s51, s11, s26
	s_add_i32 s23, s13, 0
	v_add_lshl_u32 v132, v3, v1, 1
	s_add_i32 m0, s23, 0x10000
	s_mul_i32 s9, s61, 0x2c0000
	global_load_lds_dwordx4 v132, s[50:51]
	s_add_i32 m0, s23, 0x12000
	v_mul_lo_u32 v0, v0, s4
	s_mul_hi_i32 s7, s61, 0x2c0000
	s_add_u32 s48, s20, s9
	v_add_lshl_u32 v134, v1, v0, 1
	global_load_lds_dwordx4 v128, s[50:51]
	s_addc_u32 s49, s21, s7
	s_mov_b32 m0, s23
	s_add_i32 s30, s23, 0x2000
	global_load_lds_dwordx4 v134, s[48:49]
	s_mov_b32 m0, s30
	s_add_u32 s26, s50, 0x160000
	global_load_lds_dwordx4 v130, s[48:49]
	s_addc_u32 s27, s51, 0
	s_add_i32 m0, s23, 0x14000
	v_mov_b32_e32 v133, 0
	global_load_lds_dwordx4 v132, s[26:27]
	s_add_i32 m0, s23, 0x16000
	v_mov_b32_e32 v129, v133
	global_load_lds_dwordx4 v128, s[26:27]
	s_add_u32 s26, s48, 0x160000
	s_addc_u32 s27, s49, 0
	s_add_i32 s31, s23, 0x4000
	s_mov_b32 m0, s31
	s_add_i32 s33, s23, 0x6000
	global_load_lds_dwordx4 v134, s[26:27]
	s_mov_b32 m0, s33
	v_mov_b32_e32 v135, v133
	global_load_lds_dwordx4 v130, s[26:27]
	v_mov_b32_e32 v131, v133
	v_lshl_add_u64 v[6:7], s[50:51], 0, v[132:133]
	v_lshl_add_u64 v[4:5], s[50:51], 0, v[128:129]
	v_lshl_add_u64 v[2:3], s[48:49], 0, v[134:135]
	v_lshl_add_u64 v[0:1], s[48:49], 0, v[130:131]
	s_cmp_lg_u32 s5, 1
	s_mov_b32 s9, 0x16000
	s_cbranch_scc1 .LBB0_275
	s_barrier
	s_setprio 1

; #define PG8_WAIT_V(n) asm volatile("s_waitcnt vmcnt(" #n ")" ::: "memory")
; #define PG8_BAR __builtin_amdgcn_s_barrier()
; template <class Epi>
; __device__ __forceinline__ void gemm_phase(LAS unsigned char* lds, const Gemm g, const StaticOrder& S, const Epi& E) {
;     ...
;     PG8_WAIT_V(0);
;     if (wr == 0) PG8_BAR;
;     PG8_BAR;
.LBB0_287:
	v_readlane_b32 s61, v232, 21
	s_barrier
	s_setprio 0

; __device__ __forceinline__ int fresh_tid() { int t = threadIdx.x; asm volatile("" : "+v"(t)); return t; }
; #define PG8_WAIT_V(n) asm volatile("s_waitcnt vmcnt(" #n ")" ::: "memory")
; #define PG8_BAR __builtin_amdgcn_s_barrier()
; template <class Epi>
; __device__ __forceinline__ void gemm_phase(LAS unsigned char* lds, const Gemm g, const StaticOrder& S, const Epi& E) {
;     const int tid = fresh_tid(), wid = __builtin_amdgcn_readfirstlane(tid >> 6), lane = tid & 63, wr = wid >> 2, wc = wid & 3, fr = lane & 15, fq = lane >> 4;
;     const int K = g.K, nt = K / BK;
;     unsigned voffA[2], voffB[2];
; #pragma unroll
;     for (int i = 0; i < 2; ++i) { int R, C; stage_rc(tid * 16 + i * 8192, R, C); const int Rb = (R & ~31) + perm32(R & 31);
;         voffA[i] = (unsigned)(R * K + C) * 2u; voffB[i] = (unsigned)(Rb * K + C) * 2u; }
;     const size_t kstep = (size_t)(BK * 2);
;     const size_t hstep = (size_t)HALF * K * 2;
;     const size_t tstep = 2 * hstep;
;     const unsigned ldsw = (unsigned)wid * 1024u;
;     const int aoff = lds_byte(wr * 64 + fr, fq * 8), boff = lds_byte(wc * 32 + fr, fq * 8);
;     ...
;     Unit cur, nxt; int ui = 0;
;     if (!S.next(0, cur)) return;
;     f32x4 acc[2][2][4][2];
; #pragma unroll
;     for (int a = 0; a < 2; ++a)
; #pragma unroll
;         for (int b = 0; b < 2; ++b)
; #pragma unroll
;             for (int m = 0; m < 4; ++m)
; #pragma unroll
;                 for (int n = 0; n < 2; ++n) acc[a][b][m][n] = (f32x4){0.f, 0.f, 0.f, 0.f};
;     bf16x8 At[4][2], B0[2][2], B1[2][2];
;     const char* cA = (const char*)g.A + (size_t)cur.pm * tstep; const char* cB = (const char*)g.Bt + (size_t)cur.pn * tstep;
;     PG8_STAGE(PG8_SB(0, 0), cB, voffB); PG8_STAGE(PG8_SA(0, 0), cA, voffA); PG8_STAGE(PG8_SB(0, 1), cB + hstep, voffB); PG8_STAGE(PG8_SA(0, 1), cA + hstep, voffA);
;     if (wr == 1) PG8_BAR;
;     PG8_WAIT_V(4); PG8_BAR;
;     PG8_STAGE(PG8_SB(1, 0), cB + kstep, voffB); PG8_STAGE(PG8_SA(1, 0), cA + kstep, voffA); PG8_STAGE(PG8_SB(1, 1), cB + hstep + kstep, voffB);
;     PG8_WAIT_V(6); PG8_BAR;
; __global__ __launch_bounds__(512, 2) void fwd_megakernel(Params P) {
;     ...
;     { pg8::Gemm g{HBc, (const bf16_t*)(ws + OFF_WQKV), CR, NQKV, DM}; S.init(CR, NQKV, nc, ci, 1);
;       pg8::EpiQkv E{Xc, (const float*)(ws + OFF_ROPE), (const float*)(ws + OFF_ROPE) + SEQ * 64, RSc, cls * CR}; pg8::gemm_phase(lds, g, S, E); }
.LBB0_399:
	s_or_b64 exec, exec, s[2:3]
	v_mov_b32_e32 v10, v158
	s_waitcnt lgkmcnt(0)
	s_barrier
	s_cmpk_gt_i32 s12, 0xbf
	v_readfirstlane_b32 s10, v10
	s_cbranch_scc1 .LBB0_415
	v_lshlrev_b32_e32 v0, 4, v10
	v_add_u32_e32 v1, 0x2000, v0
	v_ashrrev_i32_e32 v2, 31, v1
	v_lshrrev_b32_e32 v2, 22, v2
	v_add_u32_e32 v2, v1, v2
	v_ashrrev_i32_e32 v8, 10, v2
	v_mul_i32_i24_e32 v2, 0x400, v8
	v_sub_u32_e32 v1, v1, v2
	v_lshrrev_b32_e32 v2, 4, v1
	v_bitop3_b32 v1, v2, v1, 32 bitop3:0x6c
	v_ashrrev_i32_e32 v2, 31, v1
	v_lshrrev_b32_e32 v2, 26, v2
	v_add_u32_e32 v2, v1, v2
	v_lshlrev_b32_e32 v3, 3, v8
	v_ashrrev_i32_e32 v9, 6, v2
	v_and_b32_e32 v3, -16, v3
	v_add_u32_e32 v3, v9, v3
	v_and_b32_e32 v4, 3, v9
	s_mov_b32 s2, 0xfffe0
	v_lshrrev_b32_e32 v5, 2, v3
	v_lshlrev_b32_e32 v6, 1, v3
	v_and_b32_e32 v2, 0xc0, v2
	v_and_or_b32 v4, v3, s2, v4
	v_and_b32_e32 v5, 4, v5
	v_and_b32_e32 v6, 24, v6
	v_sub_u32_e32 v1, v1, v2
	v_mov_b32_e32 v2, 1
	v_or3_b32 v4, v4, v5, v6
	v_lshlrev_b32_e32 v5, 5, v8
	v_ashrrev_i16_sdwa v1, v2, sext(v1) dst_sel:DWORD dst_unused:UNUSED_PAD src0_sel:DWORD src1_sel:BYTE_0
	v_and_b32_e32 v5, 32, v5
	v_bfe_i32 v11, v1, 0, 16
	v_add_lshl_u32 v1, v5, v11, 1
	v_lshl_add_u32 v128, v4, 12, v1
	v_lshl_add_u32 v130, v3, 12, v1
	v_bfe_i32 v1, v10, 27, 1
	v_lshrrev_b32_e32 v1, 22, v1
	v_add_u32_e32 v1, v0, v1
	v_and_b32_e32 v1, 0xfffffc00, v1
	v_sub_u32_e32 v0, v0, v1
	v_lshrrev_b32_e32 v1, 4, v0
	v_bitop3_b32 v1, v1, v0, 32 bitop3:0x6c
	v_ashrrev_i32_e32 v0, 31, v0
	v_lshrrev_b32_e32 v0, 26, v0
	v_add_u32_e32 v0, v1, v0
	v_ashrrev_i32_e32 v12, 6, v0
	v_ashrrev_i32_e32 v0, 31, v10
	v_lshrrev_b32_e32 v0, 26, v0
	v_add_u32_e32 v0, v10, v0
	v_ashrrev_i32_e32 v13, 6, v0
	v_lshlrev_b32_e32 v0, 3, v13
	v_and_b32_e32 v0, -16, v0
	v_add_u32_e32 v0, v12, v0
	v_and_b32_e32 v3, 3, v12
	s_add_u32 s11, s16, 0x8400000
	v_and_or_b32 v3, v0, s2, v3
	s_mul_hi_i32 s2, s12, 0x2aaaaaab
	s_addc_u32 s22, s17, 0
	s_lshr_b32 s3, s2, 31
	s_ashr_i32 s2, s2, 5
	s_add_i32 s2, s2, s3
	s_lshl_b32 s3, s2, 3
	s_mulk_i32 s2, 0xc0
	s_sub_i32 s2, s12, s2
	s_bfe_u32 s4, s2, 0x3001c
	s_add_i32 s7, s2, s4
	s_sext_i32_i16 s4, s7
	s_and_b32 s7, s7, 0xfff8
	v_lshrrev_b32_e32 v4, 2, v0
	v_lshlrev_b32_e32 v5, 1, v0
	s_sub_i32 s2, s2, s7
	v_and_b32_e32 v4, 4, v4
	v_and_b32_e32 v5, 24, v5
	s_sext_i32_i16 s2, s2
	s_ashr_i32 s5, s10, 6
	v_or3_b32 v3, v3, v4, v5
	v_mul_i32_i24_e32 v5, 64, v12
	s_lshr_b32 s4, s4, 3
	s_add_i32 s44, s3, s2
	v_sub_u32_e32 v1, v1, v5
	s_ashr_i32 s45, s44, 31
	s_bfe_i64 s[8:9], s[4:5], 0x100000
	s_ashr_i32 s6, s10, 8
	s_lshl_b32 s23, s5, 10
	v_lshlrev_b32_e32 v4, 5, v13
	v_ashrrev_i16_sdwa v1, v2, sext(v1) dst_sel:DWORD dst_unused:UNUSED_PAD src0_sel:DWORD src1_sel:BYTE_0
	s_lshl_b64 s[2:3], s[44:45], 20
	s_lshl_b64 s[8:9], s[8:9], 20
	v_and_b32_e32 v4, 32, v4
	v_bfe_i32 v14, v1, 0, 16
	s_add_u32 s48, s11, s8
	v_add_lshl_u32 v1, v4, v14, 1
	s_addc_u32 s49, s22, s9
	s_add_i32 s27, s23, 0
	v_lshl_add_u32 v132, v3, 12, v1
	s_add_i32 m0, s27, 0x10000
	v_lshl_add_u32 v134, v0, 12, v1
	global_load_lds_dwordx4 v132, s[48:49]
	s_add_i32 m0, s27, 0x12000
	s_add_u32 s46, s97, s2
	global_load_lds_dwordx4 v128, s[48:49]
	s_addc_u32 s47, s94, s3
	s_mov_b32 m0, s27
	s_add_i32 s30, s27, 0x2000
	global_load_lds_dwordx4 v134, s[46:47]
	s_mov_b32 m0, s30
	s_add_u32 s2, s48, 0x80000
	global_load_lds_dwordx4 v130, s[46:47]
	s_addc_u32 s3, s49, 0
	s_add_i32 m0, s27, 0x14000
	v_mov_b32_e32 v137, 0
	global_load_lds_dwordx4 v132, s[2:3]
	s_add_i32 m0, s27, 0x16000
	v_mov_b32_e32 v133, v137
	global_load_lds_dwordx4 v128, s[2:3]
	s_add_u32 s2, s46, 0x80000
	s_addc_u32 s3, s47, 0
	s_add_i32 s31, s27, 0x4000
	s_mov_b32 m0, s31
	s_add_i32 s33, s27, 0x6000
	global_load_lds_dwordx4 v134, s[2:3]
	s_mov_b32 m0, s33
	v_mov_b32_e32 v129, v137
	global_load_lds_dwordx4 v130, s[2:3]
	v_mov_b32_e32 v135, v137
	v_mov_b32_e32 v131, v137
	s_mov_b32 s36, 0
	v_lshl_add_u64 v[6:7], s[48:49], 0, v[132:133]
	v_lshl_add_u64 v[4:5], s[48:49], 0, v[128:129]
	v_lshl_add_u64 v[2:3], s[46:47], 0, v[134:135]
	s_cmp_lg_u32 s6, 1
	v_lshl_add_u64 v[0:1], s[46:47], 0, v[130:131]
	s_cbranch_scc1 .LBB0_402
	s_barrier
	s_setprio 1

; __device__ __forceinline__ int fresh_tid() { int t = threadIdx.x; asm volatile("" : "+v"(t)); return t; }
; #define PG8_WAIT_V(n) asm volatile("s_waitcnt vmcnt(" #n ")" ::: "memory")
; #define PG8_BAR __builtin_amdgcn_s_barrier()
; template <class Epi>
; __device__ __forceinline__ void gemm_phase(LAS unsigned char* lds, const Gemm g, const StaticOrder& S, const Epi& E) {
;     const int tid = fresh_tid(), wid = __builtin_amdgcn_readfirstlane(tid >> 6), lane = tid & 63, wr = wid >> 2, wc = wid & 3, fr = lane & 15, fq = lane >> 4;
;     const int K = g.K, nt = K / BK;
;     unsigned voffA[2], voffB[2];
; #pragma unroll
;     for (int i = 0; i < 2; ++i) { int R, C; stage_rc(tid * 16 + i * 8192, R, C); const int Rb = (R & ~31) + perm32(R & 31);
;         voffA[i] = (unsigned)(R * K + C) * 2u; voffB[i] = (unsigned)(Rb * K + C) * 2u; }
;     const size_t kstep = (size_t)(BK * 2);
;     const size_t hstep = (size_t)HALF * K * 2;
;     const size_t tstep = 2 * hstep;
;     const unsigned ldsw = (unsigned)wid * 1024u;
;     const int aoff = lds_byte(wr * 64 + fr, fq * 8), boff = lds_byte(wc * 32 + fr, fq * 8);
;     ...
;     Unit cur, nxt; int ui = 0;
;     if (!S.next(0, cur)) return;
;     f32x4 acc[2][2][4][2];
; #pragma unroll
;     for (int a = 0; a < 2; ++a)
; #pragma unroll
;         for (int b = 0; b < 2; ++b)
; #pragma unroll
;             for (int m = 0; m < 4; ++m)
; #pragma unroll
;                 for (int n = 0; n < 2; ++n) acc[a][b][m][n] = (f32x4){0.f, 0.f, 0.f, 0.f};
;     bf16x8 At[4][2], B0[2][2], B1[2][2];
;     const char* cA = (const char*)g.A + (size_t)cur.pm * tstep; const char* cB = (const char*)g.Bt + (size_t)cur.pn * tstep;
;     PG8_STAGE(PG8_SB(0, 0), cB, voffB); PG8_STAGE(PG8_SA(0, 0), cA, voffA); PG8_STAGE(PG8_SB(0, 1), cB + hstep, voffB); PG8_STAGE(PG8_SA(0, 1), cA + hstep, voffA);
;     if (wr == 1) PG8_BAR;
;     PG8_WAIT_V(4); PG8_BAR;
;     PG8_STAGE(PG8_SB(1, 0), cB + kstep, voffB); PG8_STAGE(PG8_SA(1, 0), cA + kstep, voffA); PG8_STAGE(PG8_SB(1, 1), cB + hstep + kstep, voffB);
;     PG8_WAIT_V(6); PG8_BAR;
; __global__ __launch_bounds__(512, 2) void fwd_megakernel(Params P) {
;     ...
;     { pg8::Gemm g{Xc, (const bf16_t*)(ws + OFF_WO), CR, DM, DM}; S.init(CR, DM, nc, ci, 1); pg8::EpiPlain E{Fc, DM}; pg8::gemm_phase(lds, g, S, E); }
.LBB0_666:
	s_or_b64 exec, exec, s[2:3]
	v_readlane_b32 s2, v232, 18
	v_readlane_b32 s3, v232, 19
	v_mov_b32_e32 v9, v158
	s_waitcnt lgkmcnt(0)
	v_cndmask_b32_e64 v0, 0, 1, s[2:3]
	s_barrier
	v_cmp_ne_u32_e64 s[4:5], 1, v0
	s_andn2_b64 vcc, exec, s[2:3]
	v_readfirstlane_b32 s10, v9
	s_cbranch_vccnz .LBB0_678
	v_lshlrev_b32_e32 v0, 4, v9
	v_add_u32_e32 v1, 0x2000, v0
	v_ashrrev_i32_e32 v2, 31, v1
	v_lshrrev_b32_e32 v2, 22, v2
	v_add_u32_e32 v2, v1, v2
	v_ashrrev_i32_e32 v8, 10, v2
	v_mul_i32_i24_e32 v3, 0x400, v8
	v_sub_u32_e32 v1, v1, v3
	v_lshrrev_b32_e32 v3, 4, v1
	v_bitop3_b32 v1, v3, v1, 32 bitop3:0x6c
	v_ashrrev_i32_e32 v3, 31, v1
	v_lshrrev_b32_e32 v3, 26, v3
	v_add_u32_e32 v3, v1, v3
	v_ashrrev_i32_e32 v10, 6, v3
	v_and_b32_e32 v3, 0xc0, v3
	v_sub_u32_e32 v1, v1, v3
	v_mov_b32_e32 v3, 1
	v_ashrrev_i16_sdwa v1, v3, sext(v1) dst_sel:DWORD dst_unused:UNUSED_PAD src0_sel:DWORD src1_sel:BYTE_0
	v_bfe_i32 v11, v1, 0, 16
	v_lshlrev_b32_e32 v1, 3, v8
	v_and_b32_e32 v1, -16, v1
	v_add_u32_e32 v1, v10, v1
	v_lshlrev_b32_e32 v2, 5, v8
	v_and_b32_e32 v4, 3, v10
	s_mov_b32 s2, 0xfffe0
	v_lshrrev_b32_e32 v5, 2, v1
	v_lshlrev_b32_e32 v6, 1, v1
	v_and_b32_e32 v2, 32, v2
	v_and_or_b32 v4, v1, s2, v4
	v_and_b32_e32 v5, 4, v5
	v_and_b32_e32 v6, 24, v6
	v_or3_b32 v4, v4, v5, v6
	v_add_lshl_u32 v2, v2, v11, 1
	v_lshl_add_u32 v128, v4, 12, v2
	v_lshl_add_u32 v130, v1, 12, v2
	v_bfe_i32 v2, v9, 27, 1
	v_lshrrev_b32_e32 v2, 22, v2
	v_add_u32_e32 v2, v0, v2
	v_and_b32_e32 v2, 0xfffffc00, v2
	v_sub_u32_e32 v0, v0, v2
	v_lshrrev_b32_e32 v2, 4, v0
	v_bitop3_b32 v2, v2, v0, 32 bitop3:0x6c
	v_ashrrev_i32_e32 v0, 31, v0
	v_lshrrev_b32_e32 v0, 26, v0
	v_add_u32_e32 v0, v2, v0
	v_ashrrev_i32_e32 v1, 31, v9
	v_ashrrev_i32_e32 v13, 6, v0
	v_lshrrev_b32_e32 v1, 26, v1
	v_mul_i32_i24_e32 v0, 64, v13
	v_add_u32_e32 v1, v9, v1
	v_sub_u32_e32 v0, v2, v0
	v_ashrrev_i32_e32 v12, 6, v1
	v_ashrrev_i16_sdwa v0, v3, sext(v0) dst_sel:DWORD dst_unused:UNUSED_PAD src0_sel:DWORD src1_sel:BYTE_0
	v_bfe_i32 v14, v0, 0, 16
	v_lshlrev_b32_e32 v0, 3, v12
	s_add_u32 s11, s16, 0x9c00000
	v_and_b32_e32 v0, -16, v0
	s_addc_u32 s22, s17, 0
	v_add_u32_e32 v0, v13, v0
	v_and_b32_e32 v2, 3, v13
	s_ashr_i32 s27, s12, 31
	v_and_or_b32 v2, v0, s2, v2
	s_lshr_b32 s2, s27, 26
	s_add_i32 s2, s12, s2
	s_ashr_i32 s3, s2, 6
	s_and_b32 s2, s2, 0xffc0
	s_sub_i32 s2, s12, s2
	s_bfe_i32 s7, s2, 0x80000
	s_bfe_u32 s7, s7, 0x3000c
	s_add_i32 s7, s2, s7
	s_bfe_i32 s8, s7, 0x80000
	s_and_b32 s7, s7, 0xf8
	s_sub_i32 s2, s2, s7
	s_lshl_b32 s3, s3, 3
	s_sext_i32_i16 s8, s8
	s_sext_i32_i8 s2, s2
	s_ashr_i32 s9, s10, 8
	s_lshr_b32 s8, s8, 3
	s_add_i32 s48, s3, s2
	s_ashr_i32 s6, s10, 6
	s_ashr_i32 s49, s48, 31
	s_bfe_i64 s[28:29], s[8:9], 0x100000
	s_lshl_b32 s23, s6, 10
	v_lshlrev_b32_e32 v1, 5, v12
	v_lshrrev_b32_e32 v3, 2, v0
	v_lshlrev_b32_e32 v4, 1, v0
	s_lshl_b64 s[2:3], s[48:49], 20
	s_lshl_b64 s[28:29], s[28:29], 20
	v_and_b32_e32 v1, 32, v1
	v_and_b32_e32 v3, 4, v3
	v_and_b32_e32 v4, 24, v4
	s_add_u32 s52, s11, s28
	v_or3_b32 v2, v2, v3, v4
	v_add_lshl_u32 v1, v1, v14, 1
	s_addc_u32 s53, s22, s29
	s_add_i32 s28, s23, 0
	v_lshl_add_u32 v132, v2, 12, v1
	s_add_i32 m0, s28, 0x10000
	v_lshl_add_u32 v134, v0, 12, v1
	global_load_lds_dwordx4 v132, s[52:53]
	s_add_i32 m0, s28, 0x12000
	s_add_u32 s50, s20, s2
	global_load_lds_dwordx4 v128, s[52:53]
	s_addc_u32 s51, s21, s3
	s_mov_b32 m0, s28
	s_add_i32 s29, s28, 0x2000
	global_load_lds_dwordx4 v134, s[50:51]
	s_mov_b32 m0, s29
	s_add_u32 s2, s52, 0x80000
	global_load_lds_dwordx4 v130, s[50:51]
	s_addc_u32 s3, s53, 0
	s_add_i32 m0, s28, 0x14000
	v_mov_b32_e32 v133, 0
	global_load_lds_dwordx4 v132, s[2:3]
	s_add_i32 m0, s28, 0x16000
	v_mov_b32_e32 v129, v133
	global_load_lds_dwordx4 v128, s[2:3]
	s_add_u32 s2, s50, 0x80000
	s_addc_u32 s3, s51, 0
	s_add_i32 s33, s28, 0x4000
	s_mov_b32 m0, s33
	s_add_i32 s36, s28, 0x6000
	global_load_lds_dwordx4 v134, s[2:3]
	s_mov_b32 m0, s36
	v_mov_b32_e32 v135, v133
	global_load_lds_dwordx4 v130, s[2:3]
	v_mov_b32_e32 v131, v133
	s_mov_b32 s37, 0
	v_lshl_add_u64 v[6:7], s[52:53], 0, v[132:133]
	v_lshl_add_u64 v[4:5], s[52:53], 0, v[128:129]
	v_lshl_add_u64 v[2:3], s[50:51], 0, v[134:135]
	v_lshl_add_u64 v[0:1], s[50:51], 0, v[130:131]
	s_cmp_lg_u32 s9, 1
	s_mov_b64 s[2:3], 0x80000
	s_cbranch_scc1 .LBB0_669
	s_barrier
	s_setprio 1

; __device__ __forceinline__ int fresh_tid() { int t = threadIdx.x; asm volatile("" : "+v"(t)); return t; }
; #define PG8_WAIT_V(n) asm volatile("s_waitcnt vmcnt(" #n ")" ::: "memory")
; #define PG8_BAR __builtin_amdgcn_s_barrier()
; template <class Epi>
; __device__ __forceinline__ void gemm_phase(LAS unsigned char* lds, const Gemm g, const StaticOrder& S, const Epi& E) {
;     const int tid = fresh_tid(), wid = __builtin_amdgcn_readfirstlane(tid >> 6), lane = tid & 63, wr = wid >> 2, wc = wid & 3, fr = lane & 15, fq = lane >> 4;
;     const int K = g.K, nt = K / BK;
;     unsigned voffA[2], voffB[2];
; #pragma unroll
;     for (int i = 0; i < 2; ++i) { int R, C; stage_rc(tid * 16 + i * 8192, R, C); const int Rb = (R & ~31) + perm32(R & 31);
;         voffA[i] = (unsigned)(R * K + C) * 2u; voffB[i] = (unsigned)(Rb * K + C) * 2u; }
;     const size_t kstep = (size_t)(BK * 2);
;     const size_t hstep = (size_t)HALF * K * 2;
;     const size_t tstep = 2 * hstep;
;     const unsigned ldsw = (unsigned)wid * 1024u;
;     const int aoff = lds_byte(wr * 64 + fr, fq * 8), boff = lds_byte(wc * 32 + fr, fq * 8);
;     ...
;     Unit cur, nxt; int ui = 0;
;     if (!S.next(0, cur)) return;
;     f32x4 acc[2][2][4][2];
; #pragma unroll
;     for (int a = 0; a < 2; ++a)
; #pragma unroll
;         for (int b = 0; b < 2; ++b)
; #pragma unroll
;             for (int m = 0; m < 4; ++m)
; #pragma unroll
;                 for (int n = 0; n < 2; ++n) acc[a][b][m][n] = (f32x4){0.f, 0.f, 0.f, 0.f};
;     bf16x8 At[4][2], B0[2][2], B1[2][2];
;     const char* cA = (const char*)g.A + (size_t)cur.pm * tstep; const char* cB = (const char*)g.Bt + (size_t)cur.pn * tstep;
;     PG8_STAGE(PG8_SB(0, 0), cB, voffB); PG8_STAGE(PG8_SA(0, 0), cA, voffA); PG8_STAGE(PG8_SB(0, 1), cB + hstep, voffB); PG8_STAGE(PG8_SA(0, 1), cA + hstep, voffA);
;     if (wr == 1) PG8_BAR;
;     PG8_WAIT_V(4); PG8_BAR;
;     PG8_STAGE(PG8_SB(1, 0), cB + kstep, voffB); PG8_STAGE(PG8_SA(1, 0), cA + kstep, voffA); PG8_STAGE(PG8_SB(1, 1), cB + hstep + kstep, voffB);
;     PG8_WAIT_V(6); PG8_BAR;
; __global__ __launch_bounds__(512, 2) void fwd_megakernel(Params P) {
;     ...
;     { pg8::Gemm g{HBc, (const bf16_t*)(ws + OFF_W2A), CR, 2 * DFF, DM}; S.init(CR, 2 * DFF, nc, ci, 1); pg8::EpiSwiglu E{Xc, RSc}; pg8::gemm_phase(lds, g, S, E); }
.LBB0_789:
	s_or_b64 exec, exec, s[2:3]
	v_readlane_b32 s2, v232, 14
	v_mov_b32_e32 v9, v158
	v_readlane_b32 s3, v232, 15
	s_waitcnt lgkmcnt(0)
	s_barrier
	s_andn2_b64 vcc, exec, s[2:3]
	v_readfirstlane_b32 s10, v9
	s_cbranch_vccnz .LBB0_801
	v_lshlrev_b32_e32 v0, 4, v9
	v_add_u32_e32 v1, 0x2000, v0
	v_ashrrev_i32_e32 v2, 31, v1
	v_lshrrev_b32_e32 v2, 22, v2
	v_add_u32_e32 v2, v1, v2
	v_ashrrev_i32_e32 v8, 10, v2
	v_mul_i32_i24_e32 v2, 0x400, v8
	v_sub_u32_e32 v1, v1, v2
	v_lshrrev_b32_e32 v2, 4, v1
	v_bitop3_b32 v1, v2, v1, 32 bitop3:0x6c
	v_ashrrev_i32_e32 v2, 31, v1
	v_lshrrev_b32_e32 v2, 26, v2
	v_add_u32_e32 v2, v1, v2
	v_lshlrev_b32_e32 v3, 3, v8
	v_ashrrev_i32_e32 v10, 6, v2
	v_and_b32_e32 v3, -16, v3
	v_add_u32_e32 v3, v10, v3
	v_and_b32_e32 v4, 3, v10
	s_mov_b32 s3, 0xfffe0
	v_lshrrev_b32_e32 v5, 2, v3
	v_lshlrev_b32_e32 v6, 1, v3
	v_and_b32_e32 v2, 0xc0, v2
	v_and_or_b32 v4, v3, s3, v4
	v_and_b32_e32 v5, 4, v5
	v_and_b32_e32 v6, 24, v6
	v_sub_u32_e32 v1, v1, v2
	v_mov_b32_e32 v2, 1
	v_or3_b32 v4, v4, v5, v6
	v_lshlrev_b32_e32 v5, 5, v8
	v_ashrrev_i16_sdwa v1, v2, sext(v1) dst_sel:DWORD dst_unused:UNUSED_PAD src0_sel:DWORD src1_sel:BYTE_0
	v_and_b32_e32 v5, 32, v5
	v_bfe_i32 v11, v1, 0, 16
	v_add_lshl_u32 v1, v5, v11, 1
	v_lshl_add_u32 v128, v4, 12, v1
	v_lshl_add_u32 v130, v3, 12, v1
	v_bfe_i32 v1, v9, 27, 1
	v_lshrrev_b32_e32 v1, 22, v1
	v_add_u32_e32 v1, v0, v1
	v_and_b32_e32 v1, 0xfffffc00, v1
	v_sub_u32_e32 v0, v0, v1
	v_lshrrev_b32_e32 v1, 4, v0
	v_bitop3_b32 v1, v1, v0, 32 bitop3:0x6c
	v_ashrrev_i32_e32 v0, 31, v0
	v_lshrrev_b32_e32 v0, 26, v0
	v_add_u32_e32 v0, v1, v0
	v_ashrrev_i32_e32 v12, 6, v0
	v_ashrrev_i32_e32 v0, 31, v9
	v_lshrrev_b32_e32 v0, 26, v0
	v_add_u32_e32 v0, v9, v0
	v_ashrrev_i32_e32 v13, 6, v0
	v_lshlrev_b32_e32 v0, 3, v13
	v_and_b32_e32 v0, -16, v0
	s_add_u32 s11, s16, 0x4200000
	v_add_u32_e32 v0, v12, v0
	v_and_b32_e32 v3, 3, v12
	s_mul_hi_i32 s6, s12, 0x2e8ba2e9
	s_addc_u32 s22, s17, 0
	v_and_or_b32 v3, v0, s3, v3
	s_lshr_b32 s3, s6, 31
	s_ashr_i32 s6, s6, 6
	s_add_i32 s3, s6, s3
	s_lshl_b32 s8, s3, 3
	s_mulk_i32 s3, 0x160
	s_sub_i32 s3, s12, s3
	s_bfe_u32 s6, s3, 0x3001c
	s_add_i32 s9, s3, s6
	s_sext_i32_i16 s6, s9
	s_and_b32 s9, s9, 0xfff8
	v_lshrrev_b32_e32 v4, 2, v0
	v_lshlrev_b32_e32 v5, 1, v0
	s_sub_i32 s3, s3, s9
	v_and_b32_e32 v4, 4, v4
	v_and_b32_e32 v5, 24, v5
	s_sext_i32_i16 s3, s3
	s_ashr_i32 s7, s10, 8
	v_or3_b32 v3, v3, v4, v5
	v_mul_i32_i24_e32 v5, 64, v12
	s_lshr_b32 s6, s6, 3
	s_add_i32 s38, s8, s3
	s_ashr_i32 s2, s10, 6
	v_sub_u32_e32 v1, v1, v5
	s_ashr_i32 s39, s38, 31
	s_bfe_i64 s[28:29], s[6:7], 0x100000
	s_lshl_b32 s23, s2, 10
	v_lshlrev_b32_e32 v4, 5, v13
	v_ashrrev_i16_sdwa v1, v2, sext(v1) dst_sel:DWORD dst_unused:UNUSED_PAD src0_sel:DWORD src1_sel:BYTE_0
	s_lshl_b64 s[8:9], s[38:39], 20
	s_lshl_b64 s[28:29], s[28:29], 20
	v_and_b32_e32 v4, 32, v4
	v_bfe_i32 v14, v1, 0, 16
	s_add_u32 s42, s11, s28
	v_add_lshl_u32 v1, v4, v14, 1
	s_addc_u32 s43, s22, s29
	s_add_i32 s27, s23, 0
	v_lshl_add_u32 v132, v3, 12, v1
	s_add_i32 m0, s27, 0x10000
	v_lshl_add_u32 v134, v0, 12, v1
	global_load_lds_dwordx4 v132, s[42:43]
	s_add_i32 m0, s27, 0x12000
	s_add_u32 s40, s97, s8
	global_load_lds_dwordx4 v128, s[42:43]
	s_addc_u32 s41, s94, s9
	s_mov_b32 m0, s27
	s_add_i32 s28, s27, 0x2000
	global_load_lds_dwordx4 v134, s[40:41]
	s_mov_b32 m0, s28
	s_add_u32 s8, s42, 0x80000
	global_load_lds_dwordx4 v130, s[40:41]
	s_addc_u32 s9, s43, 0
	s_add_i32 m0, s27, 0x14000
	v_mov_b32_e32 v133, 0
	global_load_lds_dwordx4 v132, s[8:9]
	s_add_i32 m0, s27, 0x16000
	v_mov_b32_e32 v129, v133
	global_load_lds_dwordx4 v128, s[8:9]
	s_add_u32 s8, s40, 0x80000
	s_addc_u32 s9, s41, 0
	s_add_i32 s29, s27, 0x4000
	s_mov_b32 m0, s29
	s_add_i32 s33, s27, 0x6000
	global_load_lds_dwordx4 v134, s[8:9]
	s_mov_b32 m0, s33
	v_mov_b32_e32 v135, v133
	global_load_lds_dwordx4 v130, s[8:9]
	v_mov_b32_e32 v131, v133
	s_mov_b32 s39, 0
	v_lshl_add_u64 v[6:7], s[42:43], 0, v[132:133]
	v_lshl_add_u64 v[4:5], s[42:43], 0, v[128:129]
	v_lshl_add_u64 v[2:3], s[40:41], 0, v[134:135]
	s_cmp_lg_u32 s7, 1
	v_lshl_add_u64 v[0:1], s[40:41], 0, v[130:131]
	s_cbranch_scc1 .LBB0_792
	s_barrier
	s_setprio 1

; __device__ __forceinline__ int fresh_tid() { int t = threadIdx.x; asm volatile("" : "+v"(t)); return t; }
; #define PG8_WAIT_V(n) asm volatile("s_waitcnt vmcnt(" #n ")" ::: "memory")
; #define PG8_BAR __builtin_amdgcn_s_barrier()
; template <class Epi>
; __device__ __forceinline__ void gemm_phase(LAS unsigned char* lds, const Gemm g, const StaticOrder& S, const Epi& E) {
;     const int tid = fresh_tid(), wid = __builtin_amdgcn_readfirstlane(tid >> 6), lane = tid & 63, wr = wid >> 2, wc = wid & 3, fr = lane & 15, fq = lane >> 4;
;     const int K = g.K, nt = K / BK;
;     unsigned voffA[2], voffB[2];
; #pragma unroll
;     for (int i = 0; i < 2; ++i) { int R, C; stage_rc(tid * 16 + i * 8192, R, C); const int Rb = (R & ~31) + perm32(R & 31);
;         voffA[i] = (unsigned)(R * K + C) * 2u; voffB[i] = (unsigned)(Rb * K + C) * 2u; }
;     const size_t kstep = (size_t)(BK * 2);
;     const size_t hstep = (size_t)HALF * K * 2;
;     const size_t tstep = 2 * hstep;
;     const unsigned ldsw = (unsigned)wid * 1024u;
;     const int aoff = lds_byte(wr * 64 + fr, fq * 8), boff = lds_byte(wc * 32 + fr, fq * 8);
;     ...
;     Unit cur, nxt; int ui = 0;
;     if (!S.next(0, cur)) return;
;     f32x4 acc[2][2][4][2];
; #pragma unroll
;     for (int a = 0; a < 2; ++a)
; #pragma unroll
;         for (int b = 0; b < 2; ++b)
; #pragma unroll
;             for (int m = 0; m < 4; ++m)
; #pragma unroll
;                 for (int n = 0; n < 2; ++n) acc[a][b][m][n] = (f32x4){0.f, 0.f, 0.f, 0.f};
;     bf16x8 At[4][2], B0[2][2], B1[2][2];
;     const char* cA = (const char*)g.A + (size_t)cur.pm * tstep; const char* cB = (const char*)g.Bt + (size_t)cur.pn * tstep;
;     PG8_STAGE(PG8_SB(0, 0), cB, voffB); PG8_STAGE(PG8_SA(0, 0), cA, voffA); PG8_STAGE(PG8_SB(0, 1), cB + hstep, voffB); PG8_STAGE(PG8_SA(0, 1), cA + hstep, voffA);
;     if (wr == 1) PG8_BAR;
;     PG8_WAIT_V(4); PG8_BAR;
;     PG8_STAGE(PG8_SB(1, 0), cB + kstep, voffB); PG8_STAGE(PG8_SA(1, 0), cA + kstep, voffA); PG8_STAGE(PG8_SB(1, 1), cB + hstep + kstep, voffB);
;     PG8_WAIT_V(6); PG8_BAR;
; __global__ __launch_bounds__(512, 2) void fwd_megakernel(Params P) {
;     ...
;     { pg8::Gemm g{Xc, (const bf16_t*)(ws + OFF_W2B), CR, DM, DFF}; S.init(CR, DM, nc, ci, 1); pg8::EpiPlain E{Fc, DM}; pg8::gemm_phase(lds, g, S, E); }
.LBB0_853:
	s_or_b64 exec, exec, s[2:3]
	v_mov_b32_e32 v9, v158
	s_waitcnt lgkmcnt(0)
	s_barrier
	s_and_b64 vcc, exec, s[4:5]
	v_readfirstlane_b32 s10, v9
	s_cbranch_vccnz .LBB0_869
	v_lshlrev_b32_e32 v0, 4, v9
	v_add_u32_e32 v1, 0x2000, v0
	v_ashrrev_i32_e32 v2, 31, v1
	v_lshrrev_b32_e32 v2, 22, v2
	v_add_u32_e32 v2, v1, v2
	v_ashrrev_i32_e32 v8, 10, v2
	v_mul_i32_i24_e32 v2, 0x400, v8
	v_sub_u32_e32 v1, v1, v2
	v_lshrrev_b32_e32 v2, 4, v1
	v_bitop3_b32 v1, v2, v1, 32 bitop3:0x6c
	v_ashrrev_i32_e32 v2, 31, v1
	v_lshrrev_b32_e32 v2, 26, v2
	v_add_u32_e32 v2, v1, v2
	v_lshlrev_b32_e32 v3, 3, v8
	v_ashrrev_i32_e32 v10, 6, v2
	v_and_b32_e32 v3, -16, v3
	v_add_u32_e32 v3, v10, v3
	v_and_b32_e32 v4, 3, v10
	s_mov_b32 s3, 0x7fffe0
	v_lshrrev_b32_e32 v5, 2, v3
	v_lshlrev_b32_e32 v6, 1, v3
	v_and_b32_e32 v2, 0xc0, v2
	v_and_or_b32 v4, v3, s3, v4
	v_and_b32_e32 v5, 4, v5
	v_and_b32_e32 v6, 24, v6
	v_sub_u32_e32 v1, v1, v2
	v_mov_b32_e32 v2, 1
	v_or3_b32 v4, v4, v5, v6
	v_lshlrev_b32_e32 v5, 5, v8
	v_ashrrev_i16_sdwa v1, v2, sext(v1) dst_sel:DWORD dst_unused:UNUSED_PAD src0_sel:DWORD src1_sel:BYTE_0
	s_movk_i32 s6, 0x1600
	v_and_b32_e32 v11, 32, v5
	v_bfe_i32 v12, v1, 0, 16
	v_mul_u32_u24_e32 v4, 0x1600, v4
	v_add_u32_e32 v1, v11, v12
	v_mul_lo_u32 v3, v3, s6
	v_add_lshl_u32 v128, v4, v1, 1
	v_add_lshl_u32 v130, v1, v3, 1
	v_bfe_i32 v1, v9, 27, 1
	v_lshrrev_b32_e32 v1, 22, v1
	v_add_u32_e32 v1, v0, v1
	v_and_b32_e32 v1, 0xfffffc00, v1
	v_sub_u32_e32 v0, v0, v1
	v_lshrrev_b32_e32 v1, 4, v0
	v_bitop3_b32 v1, v1, v0, 32 bitop3:0x6c
	v_ashrrev_i32_e32 v0, 31, v0
	v_lshrrev_b32_e32 v0, 26, v0
	v_add_u32_e32 v0, v1, v0
	v_ashrrev_i32_e32 v13, 6, v0
	v_ashrrev_i32_e32 v0, 31, v9
	v_lshrrev_b32_e32 v0, 26, v0
	v_add_u32_e32 v0, v9, v0
	v_ashrrev_i32_e32 v14, 6, v0
	v_lshlrev_b32_e32 v0, 3, v14
	s_add_u32 s11, s16, 0x6e00000
	v_and_b32_e32 v0, -16, v0
	s_addc_u32 s22, s17, 0
	v_add_u32_e32 v0, v13, v0
	v_and_b32_e32 v3, 3, v13
	s_ashr_i32 s27, s12, 31
	v_and_or_b32 v3, v0, s3, v3
	s_lshr_b32 s3, s27, 26
	s_add_i32 s3, s12, s3
	s_ashr_i32 s8, s3, 6
	s_and_b32 s3, s3, 0xffc0
	s_sub_i32 s3, s12, s3
	s_lshl_b32 s9, s8, 3
	s_bfe_i32 s8, s3, 0x80000
	v_lshrrev_b32_e32 v4, 2, v0
	v_lshlrev_b32_e32 v5, 1, v0
	s_bfe_u32 s8, s8, 0x3000c
	v_and_b32_e32 v4, 4, v4
	v_and_b32_e32 v5, 24, v5
	s_add_i32 s28, s3, s8
	v_or3_b32 v3, v3, v4, v5
	v_lshlrev_b32_e32 v4, 5, v14
	s_bfe_i32 s8, s28, 0x80000
	s_and_b32 s28, s28, 0xf8
	v_and_b32_e32 v15, 32, v4
	v_mul_i32_i24_e32 v4, 64, v13
	s_sext_i32_i16 s29, s8
	s_sub_i32 s3, s3, s28
	s_ashr_i32 s2, s10, 6
	v_sub_u32_e32 v1, v1, v4
	s_sext_i32_i8 s3, s3
	s_ashr_i32 s28, s29, 3
	s_ashr_i32 s7, s10, 8
	s_lshl_b32 s23, s2, 10
	v_ashrrev_i16_sdwa v1, v2, sext(v1) dst_sel:DWORD dst_unused:UNUSED_PAD src0_sel:DWORD src1_sel:BYTE_0
	s_lshr_b32 s8, s29, 3
	s_add_i32 s63, s9, s3
	s_mul_hi_i32 s29, s28, 0x2c0000
	s_mul_i32 s28, s28, 0x2c0000
	v_bfe_i32 v16, v1, 0, 16
	s_add_u32 s44, s11, s28
	v_mul_u32_u24_e32 v3, 0x1600, v3
	v_add_u32_e32 v1, v15, v16
	s_addc_u32 s45, s22, s29
	s_add_i32 s28, s23, 0
	v_add_lshl_u32 v132, v3, v1, 1
	s_add_i32 m0, s28, 0x10000
	s_mul_i32 s9, s63, 0x2c0000
	global_load_lds_dwordx4 v132, s[44:45]
	s_add_i32 m0, s28, 0x12000
	v_mul_lo_u32 v0, v0, s6
	s_mul_hi_i32 s3, s63, 0x2c0000
	s_add_u32 s42, s20, s9
	v_add_lshl_u32 v134, v1, v0, 1
	global_load_lds_dwordx4 v128, s[44:45]
	s_addc_u32 s43, s21, s3
	s_mov_b32 m0, s28
	s_add_i32 s29, s28, 0x2000
	global_load_lds_dwordx4 v134, s[42:43]
	s_mov_b32 m0, s29
	s_add_u32 s30, s44, 0x160000
	global_load_lds_dwordx4 v130, s[42:43]
	s_addc_u32 s31, s45, 0
	s_add_i32 m0, s28, 0x14000
	v_mov_b32_e32 v133, 0
	global_load_lds_dwordx4 v132, s[30:31]
	s_add_i32 m0, s28, 0x16000
	v_mov_b32_e32 v129, v133
	global_load_lds_dwordx4 v128, s[30:31]
	s_add_u32 s30, s42, 0x160000
	s_addc_u32 s31, s43, 0
	s_add_i32 s33, s28, 0x4000
	s_mov_b32 m0, s33
	s_add_i32 s50, s28, 0x6000
	global_load_lds_dwordx4 v134, s[30:31]
	s_mov_b32 m0, s50
	v_mov_b32_e32 v135, v133
	global_load_lds_dwordx4 v130, s[30:31]
	v_mov_b32_e32 v131, v133
	s_mov_b32 s51, 0
	v_lshl_add_u64 v[6:7], s[44:45], 0, v[132:133]
	v_lshl_add_u64 v[4:5], s[44:45], 0, v[128:129]
	v_lshl_add_u64 v[2:3], s[42:43], 0, v[134:135]
	v_lshl_add_u64 v[0:1], s[42:43], 0, v[130:131]
	s_cmp_lg_u32 s7, 1
	s_mov_b32 s9, 0x16000
	s_cbranch_scc1 .LBB0_856
	s_barrier
	s_setprio 1

; __device__ __forceinline__ int fresh_tid() { int t = threadIdx.x; asm volatile("" : "+v"(t)); return t; }
; #define PG8_WAIT_V(n) asm volatile("s_waitcnt vmcnt(" #n ")" ::: "memory")
; #define PG8_BAR __builtin_amdgcn_s_barrier()
; template <class Epi>
; __device__ __forceinline__ void gemm_phase(LAS unsigned char* lds, const Gemm g, const StaticOrder& S, const Epi& E) {
;     const int tid = fresh_tid(), wid = __builtin_amdgcn_readfirstlane(tid >> 6), lane = tid & 63, wr = wid >> 2, wc = wid & 3, fr = lane & 15, fq = lane >> 4;
;     const int K = g.K, nt = K / BK;
;     unsigned voffA[2], voffB[2];
; #pragma unroll
;     for (int i = 0; i < 2; ++i) { int R, C; stage_rc(tid * 16 + i * 8192, R, C); const int Rb = (R & ~31) + perm32(R & 31);
;         voffA[i] = (unsigned)(R * K + C) * 2u; voffB[i] = (unsigned)(Rb * K + C) * 2u; }
;     const size_t kstep = (size_t)(BK * 2);
;     const size_t hstep = (size_t)HALF * K * 2;
;     const size_t tstep = 2 * hstep;
;     const unsigned ldsw = (unsigned)wid * 1024u;
;     const int aoff = lds_byte(wr * 64 + fr, fq * 8), boff = lds_byte(wc * 32 + fr, fq * 8);
;     ...
;     Unit cur, nxt; int ui = 0;
;     if (!S.next(0, cur)) return;
;     f32x4 acc[2][2][4][2];
; #pragma unroll
;     for (int a = 0; a < 2; ++a)
; #pragma unroll
;         for (int b = 0; b < 2; ++b)
; #pragma unroll
;             for (int m = 0; m < 4; ++m)
; #pragma unroll
;                 for (int n = 0; n < 2; ++n) acc[a][b][m][n] = (f32x4){0.f, 0.f, 0.f, 0.f};
;     bf16x8 At[4][2], B0[2][2], B1[2][2];
;     const char* cA = (const char*)g.A + (size_t)cur.pm * tstep; const char* cB = (const char*)g.Bt + (size_t)cur.pn * tstep;
;     PG8_STAGE(PG8_SB(0, 0), cB, voffB); PG8_STAGE(PG8_SA(0, 0), cA, voffA); PG8_STAGE(PG8_SB(0, 1), cB + hstep, voffB); PG8_STAGE(PG8_SA(0, 1), cA + hstep, voffA);
;     if (wr == 1) PG8_BAR;
;     PG8_WAIT_V(4); PG8_BAR;
;     PG8_STAGE(PG8_SB(1, 0), cB + kstep, voffB); PG8_STAGE(PG8_SA(1, 0), cA + kstep, voffA); PG8_STAGE(PG8_SB(1, 1), cB + hstep + kstep, voffB);
;     PG8_WAIT_V(6); PG8_BAR;
; __global__ __launch_bounds__(512, 2) void fwd_megakernel(Params P) {
;     ...
;     { pg8::Gemm g{(const bf16_t*)(ws + OFF_PBF) + (size_t)crow0 * PLE, (const bf16_t*)(ws + OFF_WPP), CR, DM, PLE}; S.init(CR, DM, nc, ci, 1); pg8::EpiPlain E{Xc, DM}; pg8::gemm_phase(lds, g, S, E); }
.LBB0_980:
	s_or_b64 exec, exec, s[2:3]
	v_mov_b32_e32 v8, v158
	s_waitcnt lgkmcnt(0)
	s_barrier
	s_and_b64 vcc, exec, s[4:5]
	v_readfirstlane_b32 s10, v8
	s_cbranch_vccnz .LBB0_992
	v_lshlrev_b32_e32 v0, 4, v8
	v_add_u32_e32 v1, 0x2000, v0
	v_ashrrev_i32_e32 v2, 31, v1
	v_lshrrev_b32_e32 v2, 22, v2
	v_add_u32_e32 v2, v1, v2
	v_ashrrev_i32_e32 v2, 10, v2
	v_mul_i32_i24_e32 v4, 0x400, v2
	v_sub_u32_e32 v1, v1, v4
	v_lshrrev_b32_e32 v4, 4, v1
	v_bitop3_b32 v1, v4, v1, 32 bitop3:0x6c
	v_ashrrev_i32_e32 v4, 31, v1
	v_lshrrev_b32_e32 v4, 26, v4
	v_add_u32_e32 v4, v1, v4
	v_readlane_b32 s2, v232, 9
	v_ashrrev_i32_e32 v5, 6, v4
	v_and_b32_e32 v4, 0xc0, v4
	s_lshl_b32 s2, s2, 9
	v_sub_u32_e32 v1, v1, v4
	v_mov_b32_e32 v4, 1
	s_add_u32 s2, s16, s2
	v_lshlrev_b32_e32 v3, 5, v2
	v_ashrrev_i16_sdwa v1, v4, sext(v1) dst_sel:DWORD dst_unused:UNUSED_PAD src0_sel:DWORD src1_sel:BYTE_0
	v_lshlrev_b32_e32 v2, 3, v2
	s_addc_u32 s3, s17, 0
	v_and_b32_e32 v3, 32, v3
	v_bfe_i32 v1, v1, 0, 16
	v_and_b32_e32 v2, -16, v2
	s_add_u32 s11, s2, 0xb100000
	v_add_u32_e32 v2, v5, v2
	v_add_lshl_u32 v1, v3, v1, 1
	v_bfe_i32 v3, v8, 27, 1
	s_addc_u32 s22, s3, 0
	v_and_b32_e32 v5, 3, v5
	s_mov_b32 s3, 0x7fffe0
	v_lshrrev_b32_e32 v6, 2, v2
	v_lshlrev_b32_e32 v7, 1, v2
	v_lshrrev_b32_e32 v3, 22, v3
	v_and_or_b32 v5, v2, s3, v5
	v_and_b32_e32 v6, 4, v6
	v_and_b32_e32 v7, 24, v7
	v_add_u32_e32 v3, v0, v3
	v_or3_b32 v5, v5, v6, v7
	v_and_b32_e32 v3, 0xfffffc00, v3
	v_lshl_add_u32 v128, v5, 9, v1
	v_lshl_add_u32 v130, v2, 9, v1
	v_ashrrev_i32_e32 v1, 31, v8
	v_sub_u32_e32 v0, v0, v3
	v_lshrrev_b32_e32 v1, 26, v1
	v_lshrrev_b32_e32 v3, 4, v0
	v_add_u32_e32 v1, v8, v1
	v_bitop3_b32 v3, v3, v0, 32 bitop3:0x6c
	v_ashrrev_i32_e32 v0, 31, v0
	v_ashrrev_i32_e32 v1, 6, v1
	v_lshrrev_b32_e32 v0, 26, v0
	v_lshlrev_b32_e32 v2, 5, v1
	v_add_u32_e32 v0, v3, v0
	v_lshlrev_b32_e32 v1, 3, v1
	s_add_u32 s23, s16, 0xac00000
	v_ashrrev_i32_e32 v0, 6, v0
	v_and_b32_e32 v1, -16, v1
	s_addc_u32 s27, s17, 0
	v_mul_i32_i24_e32 v5, 64, v0
	v_add_u32_e32 v1, v0, v1
	v_and_b32_e32 v0, 3, v0
	s_ashr_i32 s29, s12, 31
	v_and_or_b32 v0, v1, s3, v0
	s_lshr_b32 s3, s29, 26
	s_add_i32 s3, s12, s3
	s_ashr_i32 s6, s3, 6
	s_and_b32 s3, s3, 0xffc0
	s_sub_i32 s3, s12, s3
	s_lshl_b32 s8, s6, 3
	s_bfe_i32 s6, s3, 0x80000
	s_bfe_u32 s6, s6, 0x3000c
	s_add_i32 s9, s3, s6
	s_bfe_i32 s6, s9, 0x80000
	s_and_b32 s9, s9, 0xf8
	s_sub_i32 s3, s3, s9
	s_sext_i32_i16 s6, s6
	s_sext_i32_i8 s3, s3
	s_ashr_i32 s7, s10, 8
	s_lshr_b32 s6, s6, 3
	s_add_i32 s42, s8, s3
	s_ashr_i32 s2, s10, 6
	v_sub_u32_e32 v3, v3, v5
	s_ashr_i32 s43, s42, 31
	s_bfe_i64 s[30:31], s[6:7], 0x100000
	s_lshl_b32 s28, s2, 10
	v_ashrrev_i16_sdwa v3, v4, sext(v3) dst_sel:DWORD dst_unused:UNUSED_PAD src0_sel:DWORD src1_sel:BYTE_0
	v_lshrrev_b32_e32 v4, 2, v1
	v_lshlrev_b32_e32 v5, 1, v1
	s_lshl_b64 s[8:9], s[42:43], 17
	s_lshl_b64 s[30:31], s[30:31], 17
	v_and_b32_e32 v2, 32, v2
	v_bfe_i32 v3, v3, 0, 16
	v_and_b32_e32 v4, 4, v4
	v_and_b32_e32 v5, 24, v5
	s_add_u32 s44, s23, s30
	v_or3_b32 v0, v0, v4, v5
	v_add_lshl_u32 v2, v2, v3, 1
	s_addc_u32 s45, s27, s31
	s_add_i32 s33, s28, 0
	v_lshl_add_u32 v132, v0, 9, v2
	s_add_i32 m0, s33, 0x10000
	v_lshl_add_u32 v134, v1, 9, v2
	global_load_lds_dwordx4 v132, s[44:45]
	s_add_i32 m0, s33, 0x12000
	s_add_u32 s46, s11, s8
	global_load_lds_dwordx4 v128, s[44:45]
	s_addc_u32 s47, s22, s9
	s_mov_b32 m0, s33
	s_add_i32 s43, s33, 0x2000
	global_load_lds_dwordx4 v134, s[46:47]
	s_mov_b32 m0, s43
	s_add_u32 s8, s44, 0x10000
	global_load_lds_dwordx4 v130, s[46:47]
	s_addc_u32 s9, s45, 0
	s_add_i32 m0, s33, 0x14000
	v_mov_b32_e32 v133, 0
	global_load_lds_dwordx4 v132, s[8:9]
	s_add_i32 m0, s33, 0x16000
	v_mov_b32_e32 v129, v133
	global_load_lds_dwordx4 v128, s[8:9]
	s_add_u32 s8, s46, 0x10000
	s_addc_u32 s9, s47, 0
	s_add_i32 s62, s33, 0x4000
	s_mov_b32 m0, s62
	s_add_i32 s63, s33, 0x6000
	global_load_lds_dwordx4 v134, s[8:9]
	s_mov_b32 m0, s63
	v_mov_b32_e32 v135, v133
	global_load_lds_dwordx4 v130, s[8:9]
	v_mov_b32_e32 v131, v133
	s_mov_b32 s64, 0
	v_lshl_add_u64 v[6:7], s[44:45], 0, v[132:133]
	v_lshl_add_u64 v[4:5], s[44:45], 0, v[128:129]
	v_lshl_add_u64 v[2:3], s[46:47], 0, v[134:135]
	s_cmp_lg_u32 s7, 1
	v_lshl_add_u64 v[0:1], s[46:47], 0, v[130:131]
	s_cbranch_scc1 .LBB0_983
	s_barrier
	s_setprio 1

; #define PG8_BAR __builtin_amdgcn_s_barrier()
; template <class Epi>
; __device__ __forceinline__ void gemm_phase(LAS unsigned char* lds, const Gemm g, const StaticOrder& S, const Epi& E) {
;     const int tid = fresh_tid(), wid = __builtin_amdgcn_readfirstlane(tid >> 6), lane = tid & 63, wr = wid >> 2, wc = wid & 3, fr = lane & 15, fq = lane >> 4;
;     const int K = g.K, nt = K / BK;
;     unsigned voffA[2], voffB[2];
; #pragma unroll
;     for (int i = 0; i < 2; ++i) { int R, C; stage_rc(tid * 16 + i * 8192, R, C); const int Rb = (R & ~31) + perm32(R & 31);
;         voffA[i] = (unsigned)(R * K + C) * 2u; voffB[i] = (unsigned)(Rb * K + C) * 2u; }
;     const size_t kstep = (size_t)(BK * 2);
;     const size_t hstep = (size_t)HALF * K * 2;
;     const size_t tstep = 2 * hstep;
;     const unsigned ldsw = (unsigned)wid * 1024u;
;     const int aoff = lds_byte(wr * 64 + fr, fq * 8), boff = lds_byte(wc * 32 + fr, fq * 8);
;     ...
;     Unit cur, nxt; int ui = 0;
;     if (!S.next(0, cur)) return;
;     f32x4 acc[2][2][4][2];
; #pragma unroll
;     for (int a = 0; a < 2; ++a)
; #pragma unroll
;         for (int b = 0; b < 2; ++b)
; #pragma unroll
;             for (int m = 0; m < 4; ++m)
; #pragma unroll
;                 for (int n = 0; n < 2; ++n) acc[a][b][m][n] = (f32x4){0.f, 0.f, 0.f, 0.f};
;     bf16x8 At[4][2], B0[2][2], B1[2][2];
;     const char* cA = (const char*)g.A + (size_t)cur.pm * tstep; const char* cB = (const char*)g.Bt + (size_t)cur.pn * tstep;
;     PG8_STAGE(PG8_SB(0, 0), cB, voffB); PG8_STAGE(PG8_SA(0, 0), cA, voffA); PG8_STAGE(PG8_SB(0, 1), cB + hstep, voffB); PG8_STAGE(PG8_SA(0, 1), cA + hstep, voffA);
;     if (wr == 1) PG8_BAR;
;     PG8_WAIT_V(4); PG8_BAR;
;     PG8_STAGE(PG8_SB(1, 0), cB + kstep, voffB); PG8_STAGE(PG8_SA(1, 0), cA + kstep, voffA); PG8_STAGE(PG8_SB(1, 1), cB + hstep + kstep, voffB);
;     PG8_WAIT_V(6); PG8_BAR;
; __global__ __launch_bounds__(512, 2) void fwd_megakernel(Params P) {
;     ...
;     { pg8::Gemm g{(const bf16_t*)(ws + OFF_PBF) + (size_t)crow0 * PLE, (const bf16_t*)(ws + OFF_WPP), CR, DM, PLE}; S.init(CR, DM, nc, ci, 1); pg8::EpiPlain E{Xc, DM}; pg8::gemm_phase(lds, g, S, E); }
;     asm volatile("s_waitcnt vmcnt(0)" ::: "memory"); __syncthreads();
;     { pg8::Gemm g{HBc, (const bf16_t*)(ws + OFF_WPG), CR, DM, DM}; S.init(CR, DM, nc, ci, 1); pg8::EpiPle E{Fc, Xc, RSc}; pg8::gemm_phase(lds, g, S, E); }
.LBB0_991:
	v_readlane_b32 s74, v232, 4
	v_readlane_b32 s62, v232, 20
	v_readlane_b32 s75, v232, 5
	v_readlane_b32 s61, v232, 21
	s_barrier
	s_setprio 0
.LBB0_992:
	s_waitcnt vmcnt(0)
	v_mov_b32_e32 v9, v158
	s_waitcnt vmcnt(0) lgkmcnt(0)
	s_barrier
	s_and_b64 vcc, exec, s[4:5]
	v_readfirstlane_b32 s10, v9
	s_cbranch_vccnz .LBB0_1004
	v_lshlrev_b32_e32 v0, 4, v9
	v_add_u32_e32 v1, 0x2000, v0
	v_ashrrev_i32_e32 v2, 31, v1
	v_lshrrev_b32_e32 v2, 22, v2
	v_add_u32_e32 v2, v1, v2
	v_ashrrev_i32_e32 v8, 10, v2
	v_mul_i32_i24_e32 v2, 0x400, v8
	v_sub_u32_e32 v1, v1, v2
	v_lshrrev_b32_e32 v2, 4, v1
	v_bitop3_b32 v1, v2, v1, 32 bitop3:0x6c
	v_ashrrev_i32_e32 v2, 31, v1
	v_lshrrev_b32_e32 v2, 26, v2
	v_add_u32_e32 v2, v1, v2
	v_lshlrev_b32_e32 v3, 3, v8
	v_ashrrev_i32_e32 v10, 6, v2
	v_and_b32_e32 v3, -16, v3
	v_add_u32_e32 v3, v10, v3
	v_and_b32_e32 v4, 3, v10
	s_mov_b32 s2, 0xfffe0
	v_lshrrev_b32_e32 v5, 2, v3
	v_lshlrev_b32_e32 v6, 1, v3
	v_and_b32_e32 v2, 0xc0, v2
	v_and_or_b32 v4, v3, s2, v4
	v_and_b32_e32 v5, 4, v5
	v_and_b32_e32 v6, 24, v6
	v_sub_u32_e32 v1, v1, v2
	v_mov_b32_e32 v2, 1
	v_or3_b32 v4, v4, v5, v6
	v_lshlrev_b32_e32 v5, 5, v8
	v_ashrrev_i16_sdwa v1, v2, sext(v1) dst_sel:DWORD dst_unused:UNUSED_PAD src0_sel:DWORD src1_sel:BYTE_0
	v_and_b32_e32 v5, 32, v5
	v_bfe_i32 v11, v1, 0, 16
	v_add_lshl_u32 v1, v5, v11, 1
	v_lshl_add_u32 v128, v4, 12, v1
	v_lshl_add_u32 v130, v3, 12, v1
	v_bfe_i32 v1, v9, 27, 1
	v_lshrrev_b32_e32 v1, 22, v1
	v_add_u32_e32 v1, v0, v1
	v_and_b32_e32 v1, 0xfffffc00, v1
	v_sub_u32_e32 v0, v0, v1
	v_lshrrev_b32_e32 v1, 4, v0
	v_bitop3_b32 v1, v1, v0, 32 bitop3:0x6c
	v_ashrrev_i32_e32 v0, 31, v0
	v_lshrrev_b32_e32 v0, 26, v0
	v_add_u32_e32 v0, v1, v0
	v_ashrrev_i32_e32 v12, 6, v0
	v_ashrrev_i32_e32 v0, 31, v9
	v_lshrrev_b32_e32 v0, 26, v0
	v_add_u32_e32 v0, v9, v0
	v_ashrrev_i32_e32 v13, 6, v0
	v_lshlrev_b32_e32 v0, 3, v13
	s_add_u32 s11, s16, 0xa400000
	v_and_b32_e32 v0, -16, v0
	s_addc_u32 s22, s17, 0
	v_add_u32_e32 v0, v12, v0
	v_and_b32_e32 v3, 3, v12
	s_ashr_i32 s27, s12, 31
	v_and_or_b32 v3, v0, s2, v3
	s_lshr_b32 s2, s27, 26
	s_add_i32 s2, s12, s2
	s_ashr_i32 s3, s2, 6
	s_and_b32 s2, s2, 0xffc0
	s_sub_i32 s2, s12, s2
	s_bfe_i32 s5, s2, 0x80000
	s_bfe_u32 s5, s5, 0x3000c
	s_add_i32 s5, s2, s5
	s_bfe_i32 s6, s5, 0x80000
	s_and_b32 s5, s5, 0xf8
	v_lshrrev_b32_e32 v4, 2, v0
	v_lshlrev_b32_e32 v5, 1, v0
	s_sub_i32 s2, s2, s5
	v_and_b32_e32 v4, 4, v4
	v_and_b32_e32 v5, 24, v5
	s_lshl_b32 s3, s3, 3
	s_sext_i32_i16 s6, s6
	s_sext_i32_i8 s2, s2
	s_ashr_i32 s7, s10, 8
	v_or3_b32 v3, v3, v4, v5
	v_mul_i32_i24_e32 v5, 64, v12
	s_lshr_b32 s6, s6, 3
	s_add_i32 s44, s3, s2
	s_ashr_i32 s4, s10, 6
	v_sub_u32_e32 v1, v1, v5
	s_ashr_i32 s45, s44, 31
	s_bfe_i64 s[8:9], s[6:7], 0x100000
	s_lshl_b32 s23, s4, 10
	v_lshlrev_b32_e32 v4, 5, v13
	v_ashrrev_i16_sdwa v1, v2, sext(v1) dst_sel:DWORD dst_unused:UNUSED_PAD src0_sel:DWORD src1_sel:BYTE_0
	s_lshl_b64 s[2:3], s[44:45], 20
	s_lshl_b64 s[8:9], s[8:9], 20
	v_and_b32_e32 v4, 32, v4
	v_bfe_i32 v14, v1, 0, 16
	s_add_u32 s48, s11, s8
	v_add_lshl_u32 v1, v4, v14, 1
	s_addc_u32 s49, s22, s9
	s_add_i32 s28, s23, 0
	v_lshl_add_u32 v132, v3, 12, v1
	s_add_i32 m0, s28, 0x10000
	v_lshl_add_u32 v134, v0, 12, v1
	global_load_lds_dwordx4 v132, s[48:49]
	s_add_i32 m0, s28, 0x12000
	s_add_u32 s46, s97, s2
	global_load_lds_dwordx4 v128, s[48:49]
	s_addc_u32 s47, s94, s3
	s_mov_b32 m0, s28
	s_add_i32 s29, s28, 0x2000
	global_load_lds_dwordx4 v134, s[46:47]
	s_mov_b32 m0, s29
	s_add_u32 s2, s48, 0x80000
	global_load_lds_dwordx4 v130, s[46:47]
	s_addc_u32 s3, s49, 0
	s_add_i32 m0, s28, 0x14000
	v_mov_b32_e32 v133, 0
	global_load_lds_dwordx4 v132, s[2:3]
	s_add_i32 m0, s28, 0x16000
	v_mov_b32_e32 v129, v133
	global_load_lds_dwordx4 v128, s[2:3]
	s_add_u32 s2, s46, 0x80000
	s_addc_u32 s3, s47, 0
	s_add_i32 s33, s28, 0x4000
	s_mov_b32 m0, s33
	s_add_i32 s45, s28, 0x6000
	global_load_lds_dwordx4 v134, s[2:3]
	s_mov_b32 m0, s45
	v_mov_b32_e32 v135, v133
	global_load_lds_dwordx4 v130, s[2:3]
	v_mov_b32_e32 v131, v133
	s_mov_b32 s52, 0
	v_lshl_add_u64 v[6:7], s[48:49], 0, v[132:133]
	v_lshl_add_u64 v[4:5], s[48:49], 0, v[128:129]
	v_lshl_add_u64 v[2:3], s[46:47], 0, v[134:135]
	v_lshl_add_u64 v[0:1], s[46:47], 0, v[130:131]
	s_cmp_lg_u32 s7, 1
	s_mov_b64 s[2:3], 0x80000
	s_cbranch_scc1 .LBB0_995
	s_barrier
	s_setprio 1

; #define PG8_WAIT_V(n) asm volatile("s_waitcnt vmcnt(" #n ")" ::: "memory")
; #define PG8_BAR __builtin_amdgcn_s_barrier()
; template <class Epi>
; __device__ __forceinline__ void gemm_phase(LAS unsigned char* lds, const Gemm g, const StaticOrder& S, const Epi& E) {
;     ...
;     PG8_WAIT_V(0);
;     if (wr == 0) PG8_BAR;
;     PG8_BAR;
.LBB0_1003:
	v_readlane_b32 s62, v232, 20
	v_readlane_b32 s61, v232, 21
	s_barrier
	s_setprio 0
